# P4: both elementwise loops unrolled by two with both items' loads issued up front (two items in flight per wave)
# speedup vs baseline: 1.0056x; 1.0056x over previous
; DEVINL float bflo(unsigned u) { return __uint_as_float(u << 16); }
; DEVINL float bfhi(unsigned u) { return __uint_as_float(u & 0xffff0000u); }
; DEVINL float sigm(float x) { return 1.f / (1.f + __expf(-x)); }
; DEVINL void phase4(const Params& p) {
;     ...
;   for (int u = gw; u < T_ * 4; u += nw) {
;     const long t = u >> 2; const int h = u & 3;
;     const int c = h * 256 + lane * 4;
;     float4 o;
;     {
;       uint2 of = *(const uint2*)((const u16*)(ws + O_OSUM) + t * 1024 + c);
;       uint2 ob = *(const uint2*)((const u16*)(ws + O_OSUM) + (long)T_ * 1024 + t * 1024 + c);
;       o.x = bflo(of.x) + bflo(ob.x); o.y = bfhi(of.x) + bfhi(ob.x);
;       o.z = bflo(of.y) + bflo(ob.y); o.w = bfhi(of.y) + bfhi(ob.y);
;     }
;     float ss = o.x * o.x + o.y * o.y + o.z * o.z + o.w * o.w;
;     ss = allred64(ss);
;     const float rstd = rsqrtf(ss * (1.f / 256.f) + 1e-5f);
;     float4 ng = *(const float4*)(p.gla_norm_g + c);
;     uint2 gg = *(const uint2*)(cols + t * NCP + C_G + c);
;     float g0 = bflo(gg.x), g1 = bfhi(gg.x), g2 = bflo(gg.y), g3 = bfhi(gg.y);
;     float y0 = o.x * rstd * ng.x * (g0 * sigm(g0));
;     float y1 = o.y * rstd * ng.y * (g1 * sigm(g1));
;     float y2 = o.z * rstd * ng.z * (g2 * sigm(g2));
;     float y3 = o.w * rstd * ng.w * (g3 * sigm(g3));
;     *(uint2*)((u16*)(ws + O_YGLA) + t * 1024 + c) = make_uint2(pk2(y0, y1), pk2(y2, y3));
;   }
.LBB0_550:
	s_or_b64 exec, exec, s[0:1]
	v_mov_b32_e32 v4, v189
	s_waitcnt lgkmcnt(0)
	s_barrier
	s_lshl_b32 s52, s2, 3
	v_ashrrev_i32_e32 v3, 6, v4
	v_add_u32_e32 v2, s52, v3
	s_mov_b32 s0, 0x8000
	s_lshl_b32 s60, s94, 3
	v_cmp_gt_i32_e32 vcc, s0, v2
	s_and_saveexec_b64 s[12:13], vcc
	s_cbranch_execz .LBB0_555
	s_add_u32 s14, s92, 0x1000000
	s_addc_u32 s15, s93, 0
	v_and_b32_e32 v5, 63, v4
	s_add_u32 s16, s92, 0xf400000
	v_lshlrev_b32_e32 v0, 8, v3
	v_lshlrev_b32_e32 v6, 2, v5
	s_addc_u32 s17, s93, 0
	v_lshl_add_u32 v7, s2, 11, v0
	s_lshl_b32 s3, s94, 11
	s_mov_b64 s[18:19], 0
	s_movk_i32 s20, 0x300
	v_mov_b32_e32 v1, 0
	s_movk_i32 s21, 0x4c00
	s_mov_b32 s22, 0x4c01000
	v_mov_b32_e32 v8, 0x3727c5ac
	v_mov_b32_e32 v9, 0x3b800000
	s_mov_b32 s23, 0x800000
	s_movk_i32 s24, 0x7fff
	v_mov_b32_e32 v10, v2
	v_mov_b32_e32 v61, v1
.LBB0_552:
	v_ashrrev_i32_e32 v16, 2, v10
	v_ashrrev_i32_e32 v17, 31, v16
	v_lshlrev_b64 v[18:19], 11, v[16:17]
	v_and_or_b32 v11, v7, s20, v6
	v_lshl_add_u64 v[20:21], s[92:93], 0, v[18:19]
	v_add_u32_e32 v10, s60, v10
	v_lshlrev_b32_e32 v0, 1, v11
	v_lshl_add_u64 v[22:23], s[14:15], 0, v[18:19]
	v_mad_i64_i32 v[16:17], s[0:1], v16, s21, v[20:21]
	v_lshlrev_b32_e32 v11, 2, v11
	v_cmp_lt_i32_e32 vcc, s24, v10
	v_lshl_add_u64 v[24:25], v[20:21], 0, v[0:1]
	v_lshl_add_u64 v[22:23], v[22:23], 0, v[0:1]
	v_lshl_add_u64 v[16:17], v[16:17], 0, v[0:1]
	global_load_dwordx4 v[12:15], v11, s[88:89]
	s_or_b64 s[18:19], vcc, s[18:19]
	global_load_dwordx2 v[20:21], v[24:25], off
	s_nop 0
	global_load_dwordx2 v[22:23], v[22:23], off
	v_add_co_u32_e32 v16, vcc, s22, v16
	v_lshl_add_u64 v[18:19], s[16:17], 0, v[18:19]
	s_nop 0
	v_addc_co_u32_e32 v17, vcc, 0, v17, vcc
	global_load_dwordx2 v[16:17], v[16:17], off
	v_lshl_add_u64 v[18:19], v[18:19], 0, v[0:1]
	v_mov_b32_e32 v32, v1
	v_mov_b32_e32 v33, v1
	v_add_u32_e32 v7, s3, v7
	v_ashrrev_i32_e32 v76, 2, v10
	v_ashrrev_i32_e32 v77, 31, v76
	v_lshlrev_b64 v[78:79], 11, v[76:77]
	v_and_or_b32 v71, v7, s20, v6
	v_lshl_add_u64 v[80:81], s[92:93], 0, v[78:79]
	v_add_u32_e32 v10, s60, v10
	v_lshlrev_b32_e32 v60, 1, v71
	v_lshl_add_u64 v[82:83], s[14:15], 0, v[78:79]
	v_mad_i64_i32 v[76:77], s[0:1], v76, s21, v[80:81]
	v_lshlrev_b32_e32 v71, 2, v71
	v_cmp_lt_i32_e32 vcc, s24, v10
	v_lshl_add_u64 v[84:85], v[80:81], 0, v[60:61]
	v_lshl_add_u64 v[82:83], v[82:83], 0, v[60:61]
	v_lshl_add_u64 v[76:77], v[76:77], 0, v[60:61]
	global_load_dwordx4 v[72:75], v71, s[88:89]
	s_or_b64 s[18:19], vcc, s[18:19]
	global_load_dwordx2 v[80:81], v[84:85], off
	s_nop 0
	global_load_dwordx2 v[82:83], v[82:83], off
	v_add_co_u32_e32 v76, vcc, s22, v76
	v_lshl_add_u64 v[78:79], s[16:17], 0, v[78:79]
	s_nop 0
	v_addc_co_u32_e32 v77, vcc, 0, v77, vcc
	global_load_dwordx2 v[76:77], v[76:77], off
	v_lshl_add_u64 v[78:79], v[78:79], 0, v[60:61]
	v_mov_b32_e32 v92, v61
	v_mov_b32_e32 v93, v61
	v_add_u32_e32 v7, s3, v7
	s_waitcnt vmcnt(6)
	v_lshlrev_b32_e32 v24, 16, v20
	s_waitcnt vmcnt(5)
	v_lshlrev_b32_e32 v26, 16, v22
	v_and_b32_e32 v25, 0xffff0000, v20
	v_and_b32_e32 v27, 0xffff0000, v22
	v_lshlrev_b32_e32 v20, 16, v21
	v_lshlrev_b32_e32 v22, 16, v23
	v_and_b32_e32 v21, 0xffff0000, v21
	v_and_b32_e32 v23, 0xffff0000, v23
	v_pk_add_f32 v[20:21], v[20:21], v[22:23]
	v_pk_add_f32 v[22:23], v[24:25], v[26:27]
	s_waitcnt vmcnt(4)
	v_lshlrev_b32_e32 v24, 16, v16
	v_and_b32_e32 v25, 0xffff0000, v16
	v_pk_mul_f32 v[28:29], v[22:23], v[22:23]
	v_lshlrev_b32_e32 v16, 16, v17
	v_and_b32_e32 v17, 0xffff0000, v17
	v_pk_mul_f32 v[26:27], v[20:21], v[20:21]
	v_mul_f32_e32 v0, 0xbfb8aa3b, v24
	v_mul_f32_e32 v11, 0xbfb8aa3b, v25
	v_add_f32_e32 v30, v28, v29
	v_mul_f32_e32 v31, 0xbfb8aa3b, v16
	v_mul_f32_e32 v34, 0xbfb8aa3b, v17
	v_exp_f32_e32 v28, v0
	v_exp_f32_e32 v29, v11
	v_add_f32_e32 v0, v30, v26
	v_exp_f32_e32 v30, v31
	v_exp_f32_e32 v31, v34
	v_add_f32_e32 v0, v27, v0
	v_pk_add_f32 v[26:27], v[28:29], 1.0 op_sel_hi:[1,0]
	v_pk_add_f32 v[28:29], v[30:31], 1.0 op_sel_hi:[1,0]
	v_add_f32_dpp v0, v0, v0 quad_perm:[1,0,3,2] row_mask:0xf bank_mask:0xf bound_ctrl:1
	v_div_scale_f32 v11, s[0:1], v27, v27, 1.0
	s_nop 0
	v_add_f32_dpp v0, v0, v0 quad_perm:[2,3,0,1] row_mask:0xf bank_mask:0xf bound_ctrl:1
	v_div_scale_f32 v31, s[0:1], v26, v26, 1.0
	s_nop 0
	v_add_f32_dpp v0, v0, v0 row_half_mirror row_mask:0xf bank_mask:0xf bound_ctrl:1
	v_div_scale_f32 v35, s[6:7], v29, v29, 1.0
	s_nop 0
	v_add_f32_dpp v0, v0, v0 row_mirror row_mask:0xf bank_mask:0xf bound_ctrl:1
	v_div_scale_f32 v37, s[8:9], v28, v28, 1.0
	v_rcp_f32_e32 v39, v11
	v_mov_b32_dpp v32, v0 row_bcast:15 row_mask:0xa bank_mask:0xf
	v_rcp_f32_e32 v40, v31
	v_rcp_f32_e32 v41, v35
	v_rcp_f32_e32 v42, v37
	v_add_f32_e32 v0, v0, v32
	v_fma_f32 v32, -v11, v39, 1.0
	v_div_scale_f32 v30, vcc, 1.0, v27, 1.0
	v_mov_b32_dpp v33, v0 row_bcast:31 row_mask:0xc bank_mask:0xf
	v_add_f32_e32 v0, v0, v33
	v_fma_f32 v33, -v31, v40, 1.0
	v_readlane_b32 s10, v0, 63
	v_fma_f32 v0, -v35, v41, 1.0
	v_fma_f32 v43, -v37, v42, 1.0
	v_fmac_f32_e32 v39, v32, v39
	v_fma_f32 v32, s10, v9, v8
	v_div_scale_f32 v34, s[0:1], 1.0, v26, 1.0
	v_fmac_f32_e32 v40, v33, v40
	v_fmac_f32_e32 v41, v0, v41
	v_fmac_f32_e32 v42, v43, v42
	v_mul_f32_e32 v0, v30, v39
	v_mul_f32_e32 v43, 0x4b800000, v32
	v_cmp_gt_f32_e64 s[10:11], s23, v32
	v_div_scale_f32 v36, s[6:7], 1.0, v29, 1.0
	v_mul_f32_e32 v33, v34, v40
	v_fma_f32 v46, -v11, v0, v30
	v_cndmask_b32_e64 v32, v32, v43, s[10:11]
	v_div_scale_f32 v38, s[8:9], 1.0, v28, 1.0
	v_mul_f32_e32 v44, v36, v41
	v_fma_f32 v47, -v31, v33, v34
	v_fmac_f32_e32 v0, v46, v39
	v_rsq_f32_e32 v32, v32
	v_mul_f32_e32 v45, v38, v42
	v_fma_f32 v43, -v35, v44, v36
	v_fmac_f32_e32 v33, v47, v40
	v_fma_f32 v11, -v11, v0, v30
	v_fma_f32 v48, -v37, v45, v38
	v_fmac_f32_e32 v44, v43, v41
	v_fma_f32 v30, -v31, v33, v34
	v_div_fmas_f32 v0, v11, v39, v0
	s_mov_b64 vcc, s[0:1]
	v_fmac_f32_e32 v45, v48, v42
	v_fma_f32 v31, -v35, v44, v36
	v_div_fixup_f32 v27, v0, v27, 1.0
	v_div_fmas_f32 v0, v30, v40, v33
	s_mov_b64 vcc, s[6:7]
	v_fma_f32 v34, -v37, v45, v38
	v_div_fixup_f32 v26, v0, v26, 1.0
	v_mul_f32_e32 v0, 0x45800000, v32
	v_div_fmas_f32 v11, v31, v41, v44
	s_mov_b64 vcc, s[8:9]
	v_pk_mul_f32 v[24:25], v[26:27], v[24:25]
	v_cndmask_b32_e64 v0, v32, v0, s[10:11]
	v_div_fixup_f32 v27, v11, v29, 1.0
	v_div_fmas_f32 v11, v34, v42, v45
	v_pk_mul_f32 v[22:23], v[22:23], v[0:1] op_sel_hi:[1,0]
	v_pk_mul_f32 v[20:21], v[20:21], v[0:1] op_sel_hi:[1,0]
	v_div_fixup_f32 v26, v11, v28, 1.0
	v_pk_mul_f32 v[12:13], v[12:13], v[22:23]
	v_pk_mul_f32 v[14:15], v[14:15], v[20:21]
	v_pk_mul_f32 v[16:17], v[26:27], v[16:17]
	v_pk_mul_f32 v[12:13], v[12:13], v[24:25]
	v_pk_mul_f32 v[14:15], v[14:15], v[16:17]
	v_cvt_pk_bf16_f32 v12, v12, v13
	v_cvt_pk_bf16_f32 v13, v14, v15
	global_store_dwordx2 v[18:19], v[12:13], off
	s_waitcnt vmcnt(3)
; DEVINL float bflo(unsigned u) { return __uint_as_float(u << 16); }
; DEVINL float bfhi(unsigned u) { return __uint_as_float(u & 0xffff0000u); }
; DEVINL float sigm(float x) { return 1.f / (1.f + __expf(-x)); }
; DEVINL void phase4(const Params& p) {
;     ...
;     float ss = o.x * o.x + o.y * o.y + o.z * o.z + o.w * o.w;
;     ss = allred64(ss);
;     const float rstd = rsqrtf(ss * (1.f / 256.f) + 1e-5f);
;     float4 ng = *(const float4*)(p.gla_norm_g + c);
;     uint2 gg = *(const uint2*)(cols + t * NCP + C_G + c);
;     float g0 = bflo(gg.x), g1 = bfhi(gg.x), g2 = bflo(gg.y), g3 = bfhi(gg.y);
;     float y0 = o.x * rstd * ng.x * (g0 * sigm(g0));
;     float y1 = o.y * rstd * ng.y * (g1 * sigm(g1));
;     float y2 = o.z * rstd * ng.z * (g2 * sigm(g2));
;     float y3 = o.w * rstd * ng.w * (g3 * sigm(g3));
;     *(uint2*)((u16*)(ws + O_YGLA) + t * 1024 + c) = make_uint2(pk2(y0, y1), pk2(y2, y3));
;   }
;   for (int u = gw; u < T_ * 4; u += nw) {
;     const long t = u >> 2; const int hq = u & 3;
;     const int c = (hq * 4 + (lane >> 4)) * 64 + (lane & 15) * 4;
	v_lshlrev_b32_e32 v84, 16, v80
	s_waitcnt vmcnt(2)
	v_lshlrev_b32_e32 v86, 16, v82
	v_and_b32_e32 v85, 0xffff0000, v80
	v_and_b32_e32 v87, 0xffff0000, v82
	v_lshlrev_b32_e32 v80, 16, v81
	v_lshlrev_b32_e32 v82, 16, v83
	v_and_b32_e32 v81, 0xffff0000, v81
	v_and_b32_e32 v83, 0xffff0000, v83
	v_pk_add_f32 v[80:81], v[80:81], v[82:83]
	v_pk_add_f32 v[82:83], v[84:85], v[86:87]
	s_waitcnt vmcnt(1)
	v_lshlrev_b32_e32 v84, 16, v76
	v_and_b32_e32 v85, 0xffff0000, v76
	v_pk_mul_f32 v[88:89], v[82:83], v[82:83]
	v_lshlrev_b32_e32 v76, 16, v77
	v_and_b32_e32 v77, 0xffff0000, v77
	v_pk_mul_f32 v[86:87], v[80:81], v[80:81]
	v_mul_f32_e32 v60, 0xbfb8aa3b, v84
	v_mul_f32_e32 v71, 0xbfb8aa3b, v85
	v_add_f32_e32 v90, v88, v89
	v_mul_f32_e32 v91, 0xbfb8aa3b, v76
	v_mul_f32_e32 v94, 0xbfb8aa3b, v77
	v_exp_f32_e32 v88, v60
	v_exp_f32_e32 v89, v71
	v_add_f32_e32 v60, v90, v86
	v_exp_f32_e32 v90, v91
	v_exp_f32_e32 v91, v94
	v_add_f32_e32 v60, v87, v60
	v_pk_add_f32 v[86:87], v[88:89], 1.0 op_sel_hi:[1,0]
	v_pk_add_f32 v[88:89], v[90:91], 1.0 op_sel_hi:[1,0]
	v_add_f32_dpp v60, v60, v60 quad_perm:[1,0,3,2] row_mask:0xf bank_mask:0xf bound_ctrl:1
	v_div_scale_f32 v71, s[0:1], v87, v87, 1.0
	s_nop 0
	v_add_f32_dpp v60, v60, v60 quad_perm:[2,3,0,1] row_mask:0xf bank_mask:0xf bound_ctrl:1
	v_div_scale_f32 v91, s[0:1], v86, v86, 1.0
	s_nop 0
	v_add_f32_dpp v60, v60, v60 row_half_mirror row_mask:0xf bank_mask:0xf bound_ctrl:1
	v_div_scale_f32 v95, s[6:7], v89, v89, 1.0
	s_nop 0
	v_add_f32_dpp v60, v60, v60 row_mirror row_mask:0xf bank_mask:0xf bound_ctrl:1
	v_div_scale_f32 v97, s[8:9], v88, v88, 1.0
	v_rcp_f32_e32 v99, v71
	v_mov_b32_dpp v92, v60 row_bcast:15 row_mask:0xa bank_mask:0xf
	v_rcp_f32_e32 v100, v91
	v_rcp_f32_e32 v101, v95
	v_rcp_f32_e32 v102, v97
	v_add_f32_e32 v60, v60, v92
	v_fma_f32 v92, -v71, v99, 1.0
	v_div_scale_f32 v90, vcc, 1.0, v87, 1.0
	v_mov_b32_dpp v93, v60 row_bcast:31 row_mask:0xc bank_mask:0xf
	v_add_f32_e32 v60, v60, v93
	v_fma_f32 v93, -v91, v100, 1.0
	v_readlane_b32 s10, v60, 63
	v_fma_f32 v60, -v95, v101, 1.0
	v_fma_f32 v103, -v97, v102, 1.0
	v_fmac_f32_e32 v99, v92, v99
	v_fma_f32 v92, s10, v9, v8
	v_div_scale_f32 v94, s[0:1], 1.0, v86, 1.0
	v_fmac_f32_e32 v100, v93, v100
	v_fmac_f32_e32 v101, v60, v101
	v_fmac_f32_e32 v102, v103, v102
	v_mul_f32_e32 v60, v90, v99
	v_mul_f32_e32 v103, 0x4b800000, v92
	v_cmp_gt_f32_e64 s[10:11], s23, v92
	v_div_scale_f32 v96, s[6:7], 1.0, v89, 1.0
	v_mul_f32_e32 v93, v94, v100
	v_fma_f32 v106, -v71, v60, v90
	v_cndmask_b32_e64 v92, v92, v103, s[10:11]
	v_div_scale_f32 v98, s[8:9], 1.0, v88, 1.0
	v_mul_f32_e32 v104, v96, v101
	v_fma_f32 v107, -v91, v93, v94
	v_fmac_f32_e32 v60, v106, v99
	v_rsq_f32_e32 v92, v92
	v_mul_f32_e32 v105, v98, v102
	v_fma_f32 v103, -v95, v104, v96
	v_fmac_f32_e32 v93, v107, v100
	v_fma_f32 v71, -v71, v60, v90
	v_fma_f32 v108, -v97, v105, v98
	v_fmac_f32_e32 v104, v103, v101
	v_fma_f32 v90, -v91, v93, v94
	v_div_fmas_f32 v60, v71, v99, v60
	s_mov_b64 vcc, s[0:1]
	v_fmac_f32_e32 v105, v108, v102
	v_fma_f32 v91, -v95, v104, v96
	v_div_fixup_f32 v87, v60, v87, 1.0
	v_div_fmas_f32 v60, v90, v100, v93
	s_mov_b64 vcc, s[6:7]
	v_fma_f32 v94, -v97, v105, v98
	v_div_fixup_f32 v86, v60, v86, 1.0
	v_mul_f32_e32 v60, 0x45800000, v92
	v_div_fmas_f32 v71, v91, v101, v104
	s_mov_b64 vcc, s[8:9]
	v_pk_mul_f32 v[84:85], v[86:87], v[84:85]
	v_cndmask_b32_e64 v60, v92, v60, s[10:11]
	v_div_fixup_f32 v87, v71, v89, 1.0
	v_div_fmas_f32 v71, v94, v102, v105
	v_pk_mul_f32 v[82:83], v[82:83], v[60:61] op_sel_hi:[1,0]
	v_pk_mul_f32 v[80:81], v[80:81], v[60:61] op_sel_hi:[1,0]
	v_div_fixup_f32 v86, v71, v88, 1.0
	v_pk_mul_f32 v[72:73], v[72:73], v[82:83]
	v_pk_mul_f32 v[74:75], v[74:75], v[80:81]
	v_pk_mul_f32 v[76:77], v[86:87], v[76:77]
	v_pk_mul_f32 v[72:73], v[72:73], v[84:85]
	v_pk_mul_f32 v[74:75], v[74:75], v[76:77]
	v_cvt_pk_bf16_f32 v72, v72, v73
	v_cvt_pk_bf16_f32 v73, v74, v75
	global_store_dwordx2 v[78:79], v[72:73], off
	s_andn2_b64 exec, exec, s[18:19]
	s_cbranch_execnz .LBB0_552
	s_or_b64 exec, exec, s[18:19]
	s_add_u32 s0, s92, 0x1f700000
	s_addc_u32 s1, s93, 0
	s_add_u32 s6, s92, 0x1d500000
	s_addc_u32 s7, s93, 0
	s_add_u32 s8, s92, 0x1c500000
	v_lshlrev_b32_e32 v0, 2, v4
	s_addc_u32 s9, s93, 0
	v_and_b32_e32 v4, 60, v0
	s_add_u32 s10, s92, 0x10400000
	v_lshlrev_b32_e32 v0, 2, v3
	v_lshrrev_b32_e32 v5, 4, v5
	s_addc_u32 s11, s93, 0
	v_lshl_add_u32 v3, s2, 5, v0
	s_lshl_b32 s3, s94, 5
	s_mov_b64 s[14:15], 0
	v_mov_b32_e32 v1, 0
	v_mov_b32_e32 v6, 0x3a27c5ac
	s_mov_b32 s16, 0x800000
	s_movk_i32 s17, 0x7fff
	v_mov_b32_e32 v61, v1
; DEVINL float bflo(unsigned u) { return __uint_as_float(u << 16); }
; DEVINL float bfhi(unsigned u) { return __uint_as_float(u & 0xffff0000u); }
; DEVINL void phase4(const Params& p) {
;     ...
;   for (int u = gw; u < T_ * 4; u += nw) {
;     const long t = u >> 2; const int hq = u & 3;
;     const int c = (hq * 4 + (lane >> 4)) * 64 + (lane & 15) * 4;
;     float4 y;
;     {
;       const uint2 y1 = *(const uint2*)((const u16*)(ws + O_YSUM) + t * 1024 + c);
;       const uint2 y2 = *(const uint2*)((const u16*)(ws + O_YB) + t * 1024 + c);
;       y.x = bflo(y1.x) + bflo(y2.x); y.y = bfhi(y1.x) + bfhi(y2.x);
;       y.z = bflo(y1.y) + bflo(y2.y); y.w = bfhi(y1.y) + bfhi(y2.y);
;     }
;     float mu = allred16(y.x + y.y + y.z + y.w) * (1.f / 64.f);
;     float d0 = y.x - mu, d1 = y.y - mu, d2 = y.z - mu, d3 = y.w - mu;
;     float var = allred16(d0 * d0 + d1 * d1 + d2 * d2 + d3 * d3) * (1.f / 64.f);
.LBB0_554:
	v_ashrrev_i32_e32 v8, 2, v2
	v_and_or_b32 v0, v3, 12, v5
	v_ashrrev_i32_e32 v9, 31, v8
	v_lshl_or_b32 v7, v0, 6, v4
	v_lshlrev_b64 v[16:17], 11, v[8:9]
	v_lshlrev_b32_e32 v0, 1, v7
	v_lshl_add_u64 v[18:19], s[34:35], 0, v[16:17]
	v_lshl_add_u64 v[20:21], s[0:1], 0, v[16:17]
	v_lshl_add_u64 v[22:23], s[6:7], 0, v[16:17]
	v_lshl_add_u64 v[24:25], s[8:9], 0, v[16:17]
	v_lshlrev_b32_e32 v7, 2, v7
	v_lshl_add_u64 v[18:19], v[18:19], 0, v[0:1]
	v_lshl_add_u64 v[20:21], v[20:21], 0, v[0:1]
	v_lshl_add_u64 v[22:23], v[22:23], 0, v[0:1]
	v_lshl_add_u64 v[24:25], v[24:25], 0, v[0:1]
	global_load_dwordx4 v[8:11], v7, s[64:65]
	global_load_dwordx4 v[12:15], v7, s[66:67]
	s_nop 0
	global_load_dwordx2 v[18:19], v[18:19], off
	s_nop 0
	global_load_dwordx2 v[20:21], v[20:21], off
	s_nop 0
	global_load_dwordx2 v[22:23], v[22:23], off
	s_nop 0
	global_load_dwordx2 v[24:25], v[24:25], off
	v_lshl_add_u64 v[16:17], s[10:11], 0, v[16:17]
	v_lshl_add_u64 v[16:17], v[16:17], 0, v[0:1]
	v_add_u32_e32 v2, s60, v2
	v_cmp_lt_i32_e32 vcc, s17, v2
	s_or_b64 s[14:15], vcc, s[14:15]
	v_add_u32_e32 v3, s3, v3
	v_ashrrev_i32_e32 v68, 2, v2
	v_and_or_b32 v60, v3, 12, v5
	v_ashrrev_i32_e32 v69, 31, v68
	v_lshl_or_b32 v67, v60, 6, v4
	v_lshlrev_b64 v[76:77], 11, v[68:69]
	v_lshlrev_b32_e32 v60, 1, v67
	v_lshl_add_u64 v[78:79], s[34:35], 0, v[76:77]
	v_lshl_add_u64 v[80:81], s[0:1], 0, v[76:77]
	v_lshl_add_u64 v[82:83], s[6:7], 0, v[76:77]
	v_lshl_add_u64 v[84:85], s[8:9], 0, v[76:77]
	v_lshlrev_b32_e32 v67, 2, v67
	v_lshl_add_u64 v[78:79], v[78:79], 0, v[60:61]
	v_lshl_add_u64 v[80:81], v[80:81], 0, v[60:61]
	v_lshl_add_u64 v[82:83], v[82:83], 0, v[60:61]
	v_lshl_add_u64 v[84:85], v[84:85], 0, v[60:61]
	global_load_dwordx4 v[68:71], v67, s[64:65]
	global_load_dwordx4 v[72:75], v67, s[66:67]
	s_nop 0
	global_load_dwordx2 v[78:79], v[78:79], off
	s_nop 0
	global_load_dwordx2 v[80:81], v[80:81], off
	s_nop 0
	global_load_dwordx2 v[82:83], v[82:83], off
	s_nop 0
	global_load_dwordx2 v[84:85], v[84:85], off
	v_lshl_add_u64 v[76:77], s[10:11], 0, v[76:77]
	v_lshl_add_u64 v[76:77], v[76:77], 0, v[60:61]
	v_add_u32_e32 v2, s60, v2
	v_cmp_lt_i32_e32 vcc, s17, v2
	s_or_b64 s[14:15], vcc, s[14:15]
	v_add_u32_e32 v3, s3, v3
	s_waitcnt vmcnt(9)
	v_lshlrev_b32_e32 v26, 16, v18
	s_waitcnt vmcnt(8)
	v_lshlrev_b32_e32 v28, 16, v20
	v_and_b32_e32 v27, 0xffff0000, v18
	v_and_b32_e32 v29, 0xffff0000, v20
	v_lshlrev_b32_e32 v18, 16, v19
	v_lshlrev_b32_e32 v20, 16, v21
	v_and_b32_e32 v19, 0xffff0000, v19
	v_and_b32_e32 v21, 0xffff0000, v21
	v_pk_add_f32 v[18:19], v[18:19], v[20:21]
	v_pk_add_f32 v[20:21], v[26:27], v[28:29]
	s_waitcnt vmcnt(7)
	v_lshlrev_b32_e32 v30, 16, v22
	v_add_f32_e32 v0, v20, v21
	v_add_f32_e32 v0, v0, v18
	v_add_f32_e32 v0, v19, v0
	v_and_b32_e32 v31, 0xffff0000, v22
	v_lshlrev_b32_e32 v22, 16, v23
	v_add_f32_dpp v0, v0, v0 quad_perm:[1,0,3,2] row_mask:0xf bank_mask:0xf bound_ctrl:1
	v_and_b32_e32 v23, 0xffff0000, v23
	s_waitcnt vmcnt(6)
; DEVINL float bflo(unsigned u) { return __uint_as_float(u << 16); }
; DEVINL float bfhi(unsigned u) { return __uint_as_float(u & 0xffff0000u); }
; DEVINL void phase4(const Params& p) {
;     ...
;     float mu = allred16(y.x + y.y + y.z + y.w) * (1.f / 64.f);
;     float d0 = y.x - mu, d1 = y.y - mu, d2 = y.z - mu, d3 = y.w - mu;
;     float var = allred16(d0 * d0 + d1 * d1 + d2 * d2 + d3 * d3) * (1.f / 64.f);
;     const float rstd = rsqrtf(var + 64e-5f);
;     float4 lg = *(const float4*)(p.rw_ln_g + c);
;     float4 lb = *(const float4*)(p.rw_ln_b + c);
;     uint2 bo = *(const uint2*)((const u16*)(ws + O_BONUS) + t * 1024 + c);
;     uint2 gg = *(const uint2*)((const u16*)(ws + O_GRW) + t * 1024 + c);
;     float r0 = (d0 * rstd * lg.x + lb.x + bflo(bo.x)) * bflo(gg.x);
;     float r1 = (d1 * rstd * lg.y + lb.y + bfhi(bo.x)) * bfhi(gg.x);
;     float r2 = (d2 * rstd * lg.z + lb.z + bflo(bo.y)) * bflo(gg.y);
;     float r3 = (d3 * rstd * lg.w + lb.w + bfhi(bo.y)) * bfhi(gg.y);
;     *(uint2*)((u16*)(ws + O_YRW) + t * 1024 + c) = make_uint2(pk2(r0, r1), pk2(r2, r3));
	v_lshlrev_b32_e32 v32, 16, v24
	v_add_f32_dpp v0, v0, v0 quad_perm:[2,3,0,1] row_mask:0xf bank_mask:0xf bound_ctrl:1
	v_and_b32_e32 v33, 0xffff0000, v24
	v_lshlrev_b32_e32 v24, 16, v25
	v_add_f32_dpp v0, v0, v0 row_half_mirror row_mask:0xf bank_mask:0xf bound_ctrl:1
	v_and_b32_e32 v25, 0xffff0000, v25
	s_nop 0
	v_add_f32_dpp v0, v0, v0 row_mirror row_mask:0xf bank_mask:0xf bound_ctrl:1
	v_mul_f32_e32 v0, 0x3c800000, v0
	v_pk_add_f32 v[20:21], v[20:21], v[0:1] op_sel_hi:[1,0] neg_lo:[0,1] neg_hi:[0,1]
	v_pk_add_f32 v[18:19], v[18:19], v[0:1] op_sel_hi:[1,0] neg_lo:[0,1] neg_hi:[0,1]
	v_pk_mul_f32 v[26:27], v[20:21], v[20:21]
	v_pk_mul_f32 v[28:29], v[18:19], v[18:19]
	v_add_f32_e32 v0, v26, v27
	v_add_f32_e32 v0, v28, v0
	v_add_f32_e32 v0, v29, v0
	s_nop 1
	v_add_f32_dpp v0, v0, v0 quad_perm:[1,0,3,2] row_mask:0xf bank_mask:0xf bound_ctrl:1
	s_nop 1
	v_add_f32_dpp v0, v0, v0 quad_perm:[2,3,0,1] row_mask:0xf bank_mask:0xf bound_ctrl:1
	s_nop 1
	v_add_f32_dpp v0, v0, v0 row_half_mirror row_mask:0xf bank_mask:0xf bound_ctrl:1
	s_nop 1
	v_add_f32_dpp v0, v0, v0 row_mirror row_mask:0xf bank_mask:0xf bound_ctrl:1
	v_fmamk_f32 v0, v0, 0x3c800000, v6
	v_mul_f32_e32 v7, 0x4b800000, v0
	v_cmp_gt_f32_e32 vcc, s16, v0
	s_nop 1
	v_cndmask_b32_e32 v0, v0, v7, vcc
	v_rsq_f32_e32 v0, v0
	s_nop 0
	v_mul_f32_e32 v7, 0x45800000, v0
	v_cndmask_b32_e32 v0, v0, v7, vcc
	v_pk_mul_f32 v[20:21], v[20:21], v[0:1] op_sel_hi:[1,0]
	v_pk_mul_f32 v[18:19], v[18:19], v[0:1] op_sel_hi:[1,0]
	v_pk_fma_f32 v[8:9], v[8:9], v[20:21], v[12:13]
	v_pk_fma_f32 v[10:11], v[10:11], v[18:19], v[14:15]
	v_pk_add_f32 v[8:9], v[8:9], v[30:31]
	v_pk_add_f32 v[10:11], v[10:11], v[22:23]
	v_pk_mul_f32 v[8:9], v[8:9], v[32:33]
	v_pk_mul_f32 v[10:11], v[10:11], v[24:25]
	v_cvt_pk_bf16_f32 v8, v8, v9
	v_cvt_pk_bf16_f32 v9, v10, v11
	global_store_dwordx2 v[16:17], v[8:9], off
	s_waitcnt vmcnt(4)
	v_lshlrev_b32_e32 v86, 16, v78
	s_waitcnt vmcnt(3)
	v_lshlrev_b32_e32 v88, 16, v80
	v_and_b32_e32 v87, 0xffff0000, v78
	v_and_b32_e32 v89, 0xffff0000, v80
	v_lshlrev_b32_e32 v78, 16, v79
	v_lshlrev_b32_e32 v80, 16, v81
	v_and_b32_e32 v79, 0xffff0000, v79
	v_and_b32_e32 v81, 0xffff0000, v81
	v_pk_add_f32 v[78:79], v[78:79], v[80:81]
	v_pk_add_f32 v[80:81], v[86:87], v[88:89]
	s_waitcnt vmcnt(2)
	v_lshlrev_b32_e32 v90, 16, v82
	v_add_f32_e32 v60, v80, v81
	v_add_f32_e32 v60, v60, v78
	v_add_f32_e32 v60, v79, v60
	v_and_b32_e32 v91, 0xffff0000, v82
	v_lshlrev_b32_e32 v82, 16, v83
	v_add_f32_dpp v60, v60, v60 quad_perm:[1,0,3,2] row_mask:0xf bank_mask:0xf bound_ctrl:1
	v_and_b32_e32 v83, 0xffff0000, v83
	s_waitcnt vmcnt(1)
	v_lshlrev_b32_e32 v92, 16, v84
	v_add_f32_dpp v60, v60, v60 quad_perm:[2,3,0,1] row_mask:0xf bank_mask:0xf bound_ctrl:1
	v_and_b32_e32 v93, 0xffff0000, v84
	v_lshlrev_b32_e32 v84, 16, v85
	v_add_f32_dpp v60, v60, v60 row_half_mirror row_mask:0xf bank_mask:0xf bound_ctrl:1
	v_and_b32_e32 v85, 0xffff0000, v85
	s_nop 0
	v_add_f32_dpp v60, v60, v60 row_mirror row_mask:0xf bank_mask:0xf bound_ctrl:1
	v_mul_f32_e32 v60, 0x3c800000, v60
	v_pk_add_f32 v[80:81], v[80:81], v[60:61] op_sel_hi:[1,0] neg_lo:[0,1] neg_hi:[0,1]
	v_pk_add_f32 v[78:79], v[78:79], v[60:61] op_sel_hi:[1,0] neg_lo:[0,1] neg_hi:[0,1]
	v_pk_mul_f32 v[86:87], v[80:81], v[80:81]
	v_pk_mul_f32 v[88:89], v[78:79], v[78:79]
	v_add_f32_e32 v60, v86, v87
	v_add_f32_e32 v60, v88, v60
	v_add_f32_e32 v60, v89, v60
	s_nop 1
	v_add_f32_dpp v60, v60, v60 quad_perm:[1,0,3,2] row_mask:0xf bank_mask:0xf bound_ctrl:1
	s_nop 1
	v_add_f32_dpp v60, v60, v60 quad_perm:[2,3,0,1] row_mask:0xf bank_mask:0xf bound_ctrl:1
	s_nop 1
	v_add_f32_dpp v60, v60, v60 row_half_mirror row_mask:0xf bank_mask:0xf bound_ctrl:1
	s_nop 1
	v_add_f32_dpp v60, v60, v60 row_mirror row_mask:0xf bank_mask:0xf bound_ctrl:1
	v_fmamk_f32 v60, v60, 0x3c800000, v6
	v_mul_f32_e32 v67, 0x4b800000, v60
	v_cmp_gt_f32_e32 vcc, s16, v60
	s_nop 1
	v_cndmask_b32_e32 v60, v60, v67, vcc
	v_rsq_f32_e32 v60, v60
	s_nop 0
	v_mul_f32_e32 v67, 0x45800000, v60
	v_cndmask_b32_e32 v60, v60, v67, vcc
	v_pk_mul_f32 v[80:81], v[80:81], v[60:61] op_sel_hi:[1,0]
	v_pk_mul_f32 v[78:79], v[78:79], v[60:61] op_sel_hi:[1,0]
	v_pk_fma_f32 v[68:69], v[68:69], v[80:81], v[72:73]
	v_pk_fma_f32 v[70:71], v[70:71], v[78:79], v[74:75]
	v_pk_add_f32 v[68:69], v[68:69], v[90:91]
	v_pk_add_f32 v[70:71], v[70:71], v[82:83]
	v_pk_mul_f32 v[68:69], v[68:69], v[92:93]
	v_pk_mul_f32 v[70:71], v[70:71], v[84:85]
	v_cvt_pk_bf16_f32 v68, v68, v69
	v_cvt_pk_bf16_f32 v69, v70, v71
	global_store_dwordx2 v[76:77], v[68:69], off
	s_andn2_b64 exec, exec, s[14:15]
	s_cbranch_execnz .LBB0_554
